# baseline (speedup 1.0000x reference)
.Lidx_nostage_s0_3:
	v_max_i32_e32 v225, 0, v1
	v_fmac_f32_e32 v200, v225, v141
	v_mfma_f32_16x16x32_bf16 v[20:23], v[82:85], v[184:187], v[20:23]
	v_max_i32_e32 v224, 0, v2
	v_fmac_f32_e32 v200, v224, v142
	v_max_i32_e32 v225, 0, v3
	v_mfma_f32_16x16x32_bf16 v[28:31], v[98:101], v[184:187], v[28:31]
	ds_read_b128 v[184:187], v129 offset:10496
	v_fmac_f32_e32 v200, v225, v143
	v_max_i32_e32 v224, 0, v8
	v_fmac_f32_e32 v200, v224, v144
	v_mfma_f32_16x16x32_bf16 v[16:19], v[86:89], v[188:191], v[16:19]
	v_max_i32_e32 v225, 0, v9
	v_fmac_f32_e32 v200, v225, v145
	v_max_i32_e32 v224, 0, v10
	v_mfma_f32_16x16x32_bf16 v[24:27], v[102:105], v[188:191], v[24:27]
	ds_read_b128 v[188:191], v129 offset:12288
	v_fmac_f32_e32 v200, v224, v146
	v_max_i32_e32 v225, 0, v11
	v_fmac_f32_e32 v200, v225, v147
	v_mfma_f32_16x16x32_bf16 v[20:23], v[86:89], v[192:195], v[20:23]
	v_max_i32_e32 v224, 0, v4
	v_fma_f32 v201, v224, v140, 0
	v_max_i32_e32 v225, 0, v5
	v_mfma_f32_16x16x32_bf16 v[28:31], v[102:105], v[192:195], v[28:31]
	ds_read_b128 v[192:195], v129 offset:12544
	v_fmac_f32_e32 v201, v225, v141
	v_max_i32_e32 v224, 0, v6
	v_fmac_f32_e32 v201, v224, v142
	v_mfma_f32_16x16x32_bf16 v[16:19], v[90:93], v[196:199], v[16:19]
	v_max_i32_e32 v225, 0, v7
	v_fmac_f32_e32 v201, v225, v143
	v_max_i32_e32 v224, 0, v12
	v_mfma_f32_16x16x32_bf16 v[24:27], v[110:113], v[196:199], v[24:27]
	ds_read_b128 v[196:199], v129 offset:14336
	v_fmac_f32_e32 v201, v224, v144
	v_max_i32_e32 v225, 0, v13
	v_fmac_f32_e32 v201, v225, v145
	v_mfma_f32_16x16x32_bf16 v[20:23], v[90:93], v[226:229], v[20:23]
	v_max_i32_e32 v224, 0, v14
	v_fmac_f32_e32 v201, v224, v146
	v_mfma_f32_16x16x32_bf16 v[28:31], v[110:113], v[226:229], v[28:31]
	ds_read_b128 v[226:229], v129 offset:14592
	v_max_i32_e32 v225, 0, v15
	v_fmac_f32_e32 v201, v225, v147
	s_waitcnt lgkmcnt(7)
	v_mfma_f32_16x16x32_bf16 v[0:3], v[74:77], v[172:175], 0
	v_mfma_f32_16x16x32_bf16 v[8:11], v[62:65], v[172:175], 0
	s_waitcnt lgkmcnt(6)
	v_mfma_f32_16x16x32_bf16 v[4:7], v[74:77], v[176:179], 0
	v_mfma_f32_16x16x32_bf16 v[12:15], v[62:65], v[176:179], 0
	v_max_i32_e32 v230, 0, v16
	v_fma_f32 v202, v230, v148, 0
	s_waitcnt lgkmcnt(5)
	v_mfma_f32_16x16x32_bf16 v[0:3], v[50:53], v[180:183], v[0:3]
	v_max_i32_e32 v231, 0, v17
	v_fmac_f32_e32 v202, v231, v149
	v_mfma_f32_16x16x32_bf16 v[8:11], v[66:69], v[180:183], v[8:11]
	v_max_i32_e32 v230, 0, v18
	v_fmac_f32_e32 v202, v230, v150
	s_waitcnt lgkmcnt(4)
	v_mfma_f32_16x16x32_bf16 v[4:7], v[50:53], v[184:187], v[4:7]
	v_max_i32_e32 v231, 0, v19
	v_fmac_f32_e32 v202, v231, v151
	v_mfma_f32_16x16x32_bf16 v[12:15], v[66:69], v[184:187], v[12:15]
	v_max_i32_e32 v230, 0, v24
	v_fmac_f32_e32 v202, v230, v152
	s_waitcnt lgkmcnt(3)
	v_mfma_f32_16x16x32_bf16 v[0:3], v[54:57], v[188:191], v[0:3]
	v_max_i32_e32 v231, 0, v25
	v_fmac_f32_e32 v202, v231, v153
	v_mfma_f32_16x16x32_bf16 v[8:11], v[70:73], v[188:191], v[8:11]
	v_max_i32_e32 v230, 0, v26
	v_fmac_f32_e32 v202, v230, v154
	v_max_i32_e32 v231, 0, v27
	s_waitcnt lgkmcnt(2)
	v_mfma_f32_16x16x32_bf16 v[4:7], v[54:57], v[192:195], v[4:7]
	v_fmac_f32_e32 v202, v231, v155
	v_max_i32_e32 v230, 0, v20
	v_fma_f32 v203, v230, v148, 0
	v_mfma_f32_16x16x32_bf16 v[12:15], v[70:73], v[192:195], v[12:15]
	v_max_i32_e32 v231, 0, v21
	v_fmac_f32_e32 v203, v231, v149
	v_max_i32_e32 v230, 0, v22
	s_waitcnt lgkmcnt(1)
	v_mfma_f32_16x16x32_bf16 v[0:3], v[58:61], v[196:199], v[0:3]
	v_fmac_f32_e32 v203, v230, v150
	v_max_i32_e32 v231, 0, v23
	v_fmac_f32_e32 v203, v231, v151
	v_mfma_f32_16x16x32_bf16 v[8:11], v[78:81], v[196:199], v[8:11]
	v_max_i32_e32 v230, 0, v28
	v_fmac_f32_e32 v203, v230, v152
	v_max_i32_e32 v231, 0, v29
	s_waitcnt lgkmcnt(0)
	v_mfma_f32_16x16x32_bf16 v[4:7], v[58:61], v[226:229], v[4:7]
	v_fmac_f32_e32 v203, v231, v153
	v_max_i32_e32 v230, 0, v30
	v_fmac_f32_e32 v203, v230, v154
	v_mfma_f32_16x16x32_bf16 v[12:15], v[78:81], v[226:229], v[12:15]
	v_max_i32_e32 v231, 0, v31
	v_fmac_f32_e32 v203, v231, v155
	v_mfma_f32_16x16x32_bf16 v[16:19], v[106:109], v[172:175], 0
	v_mfma_f32_16x16x32_bf16 v[24:27], v[94:97], v[172:175], 0
	ds_read_b128 v[172:175], v129 offset:16384
	v_mfma_f32_16x16x32_bf16 v[20:23], v[106:109], v[176:179], 0
	v_mfma_f32_16x16x32_bf16 v[28:31], v[94:97], v[176:179], 0
	ds_read_b128 v[176:179], v129 offset:16640
	v_mfma_f32_16x16x32_bf16 v[16:19], v[82:85], v[180:183], v[16:19]
	v_max_i32_e32 v224, 0, v0
	v_fma_f32 v218, v224, v140, 0
	v_mfma_f32_16x16x32_bf16 v[24:27], v[98:101], v[180:183], v[24:27]
	ds_read_b128 v[180:183], v129 offset:18432
	v_max_i32_e32 v225, 0, v1
	v_fmac_f32_e32 v218, v225, v141
	v_mfma_f32_16x16x32_bf16 v[20:23], v[82:85], v[184:187], v[20:23]
	v_max_i32_e32 v224, 0, v2
	v_fmac_f32_e32 v218, v224, v142
	v_max_i32_e32 v225, 0, v3
	v_mfma_f32_16x16x32_bf16 v[28:31], v[98:101], v[184:187], v[28:31]
	ds_read_b128 v[184:187], v129 offset:18688
	v_fmac_f32_e32 v218, v225, v143
	v_max_i32_e32 v224, 0, v8
	v_fmac_f32_e32 v218, v224, v144
	v_mfma_f32_16x16x32_bf16 v[16:19], v[86:89], v[188:191], v[16:19]
	v_max_i32_e32 v225, 0, v9
	v_fmac_f32_e32 v218, v225, v145
	v_max_i32_e32 v224, 0, v10
	v_mfma_f32_16x16x32_bf16 v[24:27], v[102:105], v[188:191], v[24:27]
	ds_read_b128 v[188:191], v129 offset:20480
	v_fmac_f32_e32 v218, v224, v146
	v_max_i32_e32 v225, 0, v11
	v_fmac_f32_e32 v218, v225, v147
	v_mfma_f32_16x16x32_bf16 v[20:23], v[86:89], v[192:195], v[20:23]
	v_max_i32_e32 v224, 0, v4
	v_fma_f32 v219, v224, v140, 0
	v_max_i32_e32 v225, 0, v5
	v_mfma_f32_16x16x32_bf16 v[28:31], v[102:105], v[192:195], v[28:31]
	ds_read_b128 v[192:195], v129 offset:20736
	v_fmac_f32_e32 v219, v225, v141
	v_max_i32_e32 v224, 0, v6
	v_fmac_f32_e32 v219, v224, v142
	v_mfma_f32_16x16x32_bf16 v[16:19], v[90:93], v[196:199], v[16:19]
	v_max_i32_e32 v225, 0, v7
	v_fmac_f32_e32 v219, v225, v143
	v_max_i32_e32 v224, 0, v12
	v_mfma_f32_16x16x32_bf16 v[24:27], v[110:113], v[196:199], v[24:27]
	ds_read_b128 v[196:199], v129 offset:22528
	v_fmac_f32_e32 v219, v224, v144
	v_max_i32_e32 v225, 0, v13
	v_fmac_f32_e32 v219, v225, v145
	v_mfma_f32_16x16x32_bf16 v[20:23], v[90:93], v[226:229], v[20:23]
	v_max_i32_e32 v224, 0, v14
	v_fmac_f32_e32 v219, v224, v146
	v_mfma_f32_16x16x32_bf16 v[28:31], v[110:113], v[226:229], v[28:31]
	ds_read_b128 v[226:229], v129 offset:22784
	v_max_i32_e32 v225, 0, v15
	v_fmac_f32_e32 v219, v225, v147
	s_waitcnt lgkmcnt(7)
; __device__ __forceinline__ void ph_indexer(const Params& p, char* shm) {
;     ...
;           IDX_TILE(ktp * 2, pr0);
;           __builtin_amdgcn_sched_barrier(0);
;           IDX_TILE(ktp * 2 + 1, pr1);
;           __builtin_amdgcn_sched_barrier(0);
;     ...
; #pragma unroll
;           for (int q = 0; q < 2; ++q) {
;             const float mine = half ? pr1[q] : pr0[q];
;             const float send = half ? pr0[q] : pr1[q];
;             const float recv = __shfl_xor(send, 32);
;             p.SC[(rowb + wid * 2 + q) * L + st * 128 + ktp * 64 + lane] = mine + recv;
;           }
	v_mfma_f32_16x16x32_bf16 v[0:3], v[74:77], v[172:175], 0
	v_mfma_f32_16x16x32_bf16 v[8:11], v[62:65], v[172:175], 0
	s_waitcnt lgkmcnt(6)
	v_mfma_f32_16x16x32_bf16 v[4:7], v[74:77], v[176:179], 0
	v_mfma_f32_16x16x32_bf16 v[12:15], v[62:65], v[176:179], 0
	v_max_i32_e32 v230, 0, v16
	v_fma_f32 v220, v230, v148, 0
	s_waitcnt lgkmcnt(5)
	v_mfma_f32_16x16x32_bf16 v[0:3], v[50:53], v[180:183], v[0:3]
	v_max_i32_e32 v231, 0, v17
	v_fmac_f32_e32 v220, v231, v149
	v_mfma_f32_16x16x32_bf16 v[8:11], v[66:69], v[180:183], v[8:11]
	v_max_i32_e32 v230, 0, v18
	v_fmac_f32_e32 v220, v230, v150
	s_waitcnt lgkmcnt(4)
	v_mfma_f32_16x16x32_bf16 v[4:7], v[50:53], v[184:187], v[4:7]
	v_max_i32_e32 v231, 0, v19
	v_fmac_f32_e32 v220, v231, v151
	v_mfma_f32_16x16x32_bf16 v[12:15], v[66:69], v[184:187], v[12:15]
	v_max_i32_e32 v230, 0, v24
	v_fmac_f32_e32 v220, v230, v152
	s_waitcnt lgkmcnt(3)
	v_mfma_f32_16x16x32_bf16 v[0:3], v[54:57], v[188:191], v[0:3]
	v_max_i32_e32 v231, 0, v25
	v_fmac_f32_e32 v220, v231, v153
	v_mfma_f32_16x16x32_bf16 v[8:11], v[70:73], v[188:191], v[8:11]
	v_max_i32_e32 v230, 0, v26
	v_fmac_f32_e32 v220, v230, v154
	v_max_i32_e32 v231, 0, v27
	s_waitcnt lgkmcnt(2)
	v_mfma_f32_16x16x32_bf16 v[4:7], v[54:57], v[192:195], v[4:7]
	v_fmac_f32_e32 v220, v231, v155
	v_max_i32_e32 v230, 0, v20
	v_fma_f32 v221, v230, v148, 0
	v_mfma_f32_16x16x32_bf16 v[12:15], v[70:73], v[192:195], v[12:15]
	v_max_i32_e32 v231, 0, v21
	v_fmac_f32_e32 v221, v231, v149
	v_max_i32_e32 v230, 0, v22
	s_waitcnt lgkmcnt(1)
	v_mfma_f32_16x16x32_bf16 v[0:3], v[58:61], v[196:199], v[0:3]
	v_fmac_f32_e32 v221, v230, v150
	v_max_i32_e32 v231, 0, v23
	v_fmac_f32_e32 v221, v231, v151
	v_mfma_f32_16x16x32_bf16 v[8:11], v[78:81], v[196:199], v[8:11]
	v_max_i32_e32 v230, 0, v28
	v_fmac_f32_e32 v221, v230, v152
	v_max_i32_e32 v231, 0, v29
	s_waitcnt lgkmcnt(0)
	v_mfma_f32_16x16x32_bf16 v[4:7], v[58:61], v[226:229], v[4:7]
	v_fmac_f32_e32 v221, v231, v153
	v_max_i32_e32 v230, 0, v30
	v_fmac_f32_e32 v221, v230, v154
	v_mfma_f32_16x16x32_bf16 v[12:15], v[78:81], v[226:229], v[12:15]
	v_max_i32_e32 v231, 0, v31
	v_fmac_f32_e32 v221, v231, v155
	v_mfma_f32_16x16x32_bf16 v[16:19], v[106:109], v[172:175], 0
	s_nop 1
	v_permlane16_swap_b32_e32 v200, v201
	v_permlane16_swap_b32_e32 v218, v219
	v_permlane16_swap_b32_e32 v202, v203
	v_mfma_f32_16x16x32_bf16 v[24:27], v[94:97], v[172:175], 0
	ds_read_b128 v[172:175], v129 offset:24576
	v_permlane16_swap_b32_e32 v220, v221
	v_add_f32_e32 v200, v200, v201
	v_add_f32_e32 v218, v218, v219
	v_add_f32_e32 v202, v202, v203
	v_mfma_f32_16x16x32_bf16 v[20:23], v[106:109], v[176:179], 0
	v_add_f32_e32 v220, v220, v221
	s_nop 1
	v_permlane32_swap_b32_e32 v200, v218
	v_permlane32_swap_b32_e32 v202, v220
	v_mfma_f32_16x16x32_bf16 v[28:31], v[94:97], v[176:179], 0
	ds_read_b128 v[176:179], v129 offset:24832
	v_add_f32_e32 v200, v200, v218
	v_add_f32_e32 v202, v202, v220
	global_store_dword v[232:233], v200, off nt
	global_store_dword v[234:235], v202, off nt
	v_mfma_f32_16x16x32_bf16 v[16:19], v[82:85], v[180:183], v[16:19]
	v_max_i32_e32 v224, 0, v0
	v_fma_f32 v222, v224, v140, 0
	v_mfma_f32_16x16x32_bf16 v[24:27], v[98:101], v[180:183], v[24:27]
	ds_read_b128 v[180:183], v129 offset:26624
	v_max_i32_e32 v225, 0, v1
	v_fmac_f32_e32 v222, v225, v141
	v_mfma_f32_16x16x32_bf16 v[20:23], v[82:85], v[184:187], v[20:23]
	v_max_i32_e32 v224, 0, v2
	v_fmac_f32_e32 v222, v224, v142
	v_max_i32_e32 v225, 0, v3
	v_mfma_f32_16x16x32_bf16 v[28:31], v[98:101], v[184:187], v[28:31]
	ds_read_b128 v[184:187], v129 offset:26880
	v_fmac_f32_e32 v222, v225, v143
	v_max_i32_e32 v224, 0, v8
	v_fmac_f32_e32 v222, v224, v144
	v_mfma_f32_16x16x32_bf16 v[16:19], v[86:89], v[188:191], v[16:19]
	v_max_i32_e32 v225, 0, v9
	v_fmac_f32_e32 v222, v225, v145
	v_max_i32_e32 v224, 0, v10
	v_mfma_f32_16x16x32_bf16 v[24:27], v[102:105], v[188:191], v[24:27]
	ds_read_b128 v[188:191], v129 offset:28672
	v_fmac_f32_e32 v222, v224, v146
	v_max_i32_e32 v225, 0, v11
	v_fmac_f32_e32 v222, v225, v147
	v_mfma_f32_16x16x32_bf16 v[20:23], v[86:89], v[192:195], v[20:23]
	v_max_i32_e32 v224, 0, v4
	v_fma_f32 v223, v224, v140, 0
	v_max_i32_e32 v225, 0, v5
	v_mfma_f32_16x16x32_bf16 v[28:31], v[102:105], v[192:195], v[28:31]
	ds_read_b128 v[192:195], v129 offset:28928
	v_fmac_f32_e32 v223, v225, v141
	v_max_i32_e32 v224, 0, v6
	v_fmac_f32_e32 v223, v224, v142
	v_mfma_f32_16x16x32_bf16 v[16:19], v[90:93], v[196:199], v[16:19]
	v_max_i32_e32 v225, 0, v7
	v_fmac_f32_e32 v223, v225, v143
	v_max_i32_e32 v224, 0, v12
	v_mfma_f32_16x16x32_bf16 v[24:27], v[110:113], v[196:199], v[24:27]
	ds_read_b128 v[196:199], v129 offset:30720
	v_fmac_f32_e32 v223, v224, v144
	v_max_i32_e32 v225, 0, v13
	v_fmac_f32_e32 v223, v225, v145
	v_mfma_f32_16x16x32_bf16 v[20:23], v[90:93], v[226:229], v[20:23]
	v_max_i32_e32 v224, 0, v14
	v_fmac_f32_e32 v223, v224, v146
	v_mfma_f32_16x16x32_bf16 v[28:31], v[110:113], v[226:229], v[28:31]
	ds_read_b128 v[226:229], v129 offset:30976
	v_max_i32_e32 v225, 0, v15
	v_fmac_f32_e32 v223, v225, v147
	s_waitcnt lgkmcnt(7)
; #define WAIT_V0() asm volatile("s_waitcnt vmcnt(0)" ::: "memory")
; #define WAIT_L0() asm volatile("s_waitcnt lgkmcnt(0)" ::: "memory")
; __device__ __forceinline__ void ph_indexer(const Params& p, char* shm) {
;     ...
;       for (int st = 0; st < nst; ++st) {
;         if (st == 0) WAIT_V0(); else asm volatile("s_waitcnt vmcnt(4)" ::: "memory");
;         WAIT_L0();
;         __builtin_amdgcn_s_barrier();
;         if (st + 1 < nst) IDX_STAGE((st + 1) & 1, st + 1);
	v_mfma_f32_16x16x32_bf16 v[0:3], v[74:77], v[172:175], 0
	v_mfma_f32_16x16x32_bf16 v[8:11], v[62:65], v[172:175], 0
	s_waitcnt lgkmcnt(6)
	v_mfma_f32_16x16x32_bf16 v[4:7], v[74:77], v[176:179], 0
	v_mfma_f32_16x16x32_bf16 v[12:15], v[62:65], v[176:179], 0
	v_max_i32_e32 v230, 0, v16
	v_fma_f32 v202, v230, v148, 0
	s_waitcnt lgkmcnt(5)
	v_mfma_f32_16x16x32_bf16 v[0:3], v[50:53], v[180:183], v[0:3]
	v_max_i32_e32 v231, 0, v17
	v_fmac_f32_e32 v202, v231, v149
	v_mfma_f32_16x16x32_bf16 v[8:11], v[66:69], v[180:183], v[8:11]
	v_max_i32_e32 v230, 0, v18
	v_fmac_f32_e32 v202, v230, v150
	s_waitcnt lgkmcnt(4)
	v_mfma_f32_16x16x32_bf16 v[4:7], v[50:53], v[184:187], v[4:7]
	v_max_i32_e32 v231, 0, v19
	v_fmac_f32_e32 v202, v231, v151
	v_mfma_f32_16x16x32_bf16 v[12:15], v[66:69], v[184:187], v[12:15]
	v_max_i32_e32 v230, 0, v24
	v_fmac_f32_e32 v202, v230, v152
	s_waitcnt lgkmcnt(3)
	v_mfma_f32_16x16x32_bf16 v[0:3], v[54:57], v[188:191], v[0:3]
	v_max_i32_e32 v231, 0, v25
	v_fmac_f32_e32 v202, v231, v153
	v_mfma_f32_16x16x32_bf16 v[8:11], v[70:73], v[188:191], v[8:11]
	v_max_i32_e32 v230, 0, v26
	v_fmac_f32_e32 v202, v230, v154
	v_max_i32_e32 v231, 0, v27
	s_waitcnt lgkmcnt(2)
	v_mfma_f32_16x16x32_bf16 v[4:7], v[54:57], v[192:195], v[4:7]
	v_fmac_f32_e32 v202, v231, v155
	v_max_i32_e32 v230, 0, v20
	v_fma_f32 v203, v230, v148, 0
	v_mfma_f32_16x16x32_bf16 v[12:15], v[70:73], v[192:195], v[12:15]
	v_max_i32_e32 v231, 0, v21
	v_fmac_f32_e32 v203, v231, v149
	v_max_i32_e32 v230, 0, v22
	s_waitcnt lgkmcnt(1)
	v_mfma_f32_16x16x32_bf16 v[0:3], v[58:61], v[196:199], v[0:3]
	v_fmac_f32_e32 v203, v230, v150
	v_max_i32_e32 v231, 0, v23
	v_fmac_f32_e32 v203, v231, v151
	v_mfma_f32_16x16x32_bf16 v[8:11], v[78:81], v[196:199], v[8:11]
	v_max_i32_e32 v230, 0, v28
	v_fmac_f32_e32 v203, v230, v152
	v_max_i32_e32 v231, 0, v29
	s_waitcnt lgkmcnt(0)
	v_mfma_f32_16x16x32_bf16 v[4:7], v[58:61], v[226:229], v[4:7]
	v_fmac_f32_e32 v203, v231, v153
	v_max_i32_e32 v230, 0, v30
	v_fmac_f32_e32 v203, v230, v154
	v_mfma_f32_16x16x32_bf16 v[12:15], v[78:81], v[226:229], v[12:15]
	v_max_i32_e32 v231, 0, v31
	v_fmac_f32_e32 v203, v231, v155
	v_mfma_f32_16x16x32_bf16 v[16:19], v[106:109], v[172:175], 0
	v_mfma_f32_16x16x32_bf16 v[24:27], v[94:97], v[172:175], 0
	v_mfma_f32_16x16x32_bf16 v[20:23], v[106:109], v[176:179], 0
	v_mfma_f32_16x16x32_bf16 v[28:31], v[94:97], v[176:179], 0
	v_mfma_f32_16x16x32_bf16 v[16:19], v[82:85], v[180:183], v[16:19]
	v_max_i32_e32 v224, 0, v0
	v_fma_f32 v218, v224, v140, 0
	v_mfma_f32_16x16x32_bf16 v[24:27], v[98:101], v[180:183], v[24:27]
	v_max_i32_e32 v225, 0, v1
	v_fmac_f32_e32 v218, v225, v141
	v_mfma_f32_16x16x32_bf16 v[20:23], v[82:85], v[184:187], v[20:23]
	v_max_i32_e32 v224, 0, v2
	v_fmac_f32_e32 v218, v224, v142
	v_max_i32_e32 v225, 0, v3
	v_mfma_f32_16x16x32_bf16 v[28:31], v[98:101], v[184:187], v[28:31]
	v_fmac_f32_e32 v218, v225, v143
	v_max_i32_e32 v224, 0, v8
	v_fmac_f32_e32 v218, v224, v144
	v_mfma_f32_16x16x32_bf16 v[16:19], v[86:89], v[188:191], v[16:19]
	v_max_i32_e32 v225, 0, v9
	v_fmac_f32_e32 v218, v225, v145
	v_max_i32_e32 v224, 0, v10
	v_mfma_f32_16x16x32_bf16 v[24:27], v[102:105], v[188:191], v[24:27]
	v_fmac_f32_e32 v218, v224, v146
	v_max_i32_e32 v225, 0, v11
	v_fmac_f32_e32 v218, v225, v147
	v_mfma_f32_16x16x32_bf16 v[20:23], v[86:89], v[192:195], v[20:23]
	v_max_i32_e32 v224, 0, v4
	v_fma_f32 v219, v224, v140, 0
	v_max_i32_e32 v225, 0, v5
	v_mfma_f32_16x16x32_bf16 v[28:31], v[102:105], v[192:195], v[28:31]
	v_fmac_f32_e32 v219, v225, v141
	v_max_i32_e32 v224, 0, v6
	v_fmac_f32_e32 v219, v224, v142
	v_mfma_f32_16x16x32_bf16 v[16:19], v[90:93], v[196:199], v[16:19]
	v_max_i32_e32 v225, 0, v7
	v_fmac_f32_e32 v219, v225, v143
	v_max_i32_e32 v224, 0, v12
	v_mfma_f32_16x16x32_bf16 v[24:27], v[110:113], v[196:199], v[24:27]
	v_fmac_f32_e32 v219, v224, v144
	v_max_i32_e32 v225, 0, v13
	v_fmac_f32_e32 v219, v225, v145
	v_mfma_f32_16x16x32_bf16 v[20:23], v[90:93], v[226:229], v[20:23]
	v_max_i32_e32 v224, 0, v14
	v_fmac_f32_e32 v219, v224, v146
	v_mfma_f32_16x16x32_bf16 v[28:31], v[110:113], v[226:229], v[28:31]
	v_max_i32_e32 v225, 0, v15
	v_fmac_f32_e32 v219, v225, v147
	s_cmp_lg_u32 s22, s44
	s_cbranch_scc0 .Lidx_flush_s0
	s_mov_b32 s4, s22
	s_waitcnt vmcnt(2)
	s_waitcnt lgkmcnt(0)
	s_add_i32 s22, s4, 1
	s_barrier
	s_branch .LBB0_928

.Lidx_nostage_s1_3:
	v_max_i32_e32 v225, 0, v1
	v_fmac_f32_e32 v200, v225, v129
	v_mfma_f32_16x16x32_bf16 v[188:191], v[66:69], v[172:175], v[188:191]
	v_max_i32_e32 v224, 0, v2
	v_fmac_f32_e32 v200, v224, v130
	v_max_i32_e32 v225, 0, v3
	v_mfma_f32_16x16x32_bf16 v[196:199], v[82:85], v[172:175], v[196:199]
	ds_read_b128 v[172:175], v112 offset:10496
	v_fmac_f32_e32 v200, v225, v131
	v_max_i32_e32 v224, 0, v8
	v_fmac_f32_e32 v200, v224, v132
	v_mfma_f32_16x16x32_bf16 v[184:187], v[70:73], v[176:179], v[184:187]
	v_max_i32_e32 v225, 0, v9
	v_fmac_f32_e32 v200, v225, v133
	v_max_i32_e32 v224, 0, v10
	v_mfma_f32_16x16x32_bf16 v[192:195], v[86:89], v[176:179], v[192:195]
	ds_read_b128 v[176:179], v112 offset:12288
	v_fmac_f32_e32 v200, v224, v134
	v_max_i32_e32 v225, 0, v11
	v_fmac_f32_e32 v200, v225, v135
	v_mfma_f32_16x16x32_bf16 v[188:191], v[70:73], v[106:109], v[188:191]
	v_max_i32_e32 v224, 0, v4
	v_fma_f32 v201, v224, v128, 0
	v_max_i32_e32 v225, 0, v5
	v_mfma_f32_16x16x32_bf16 v[196:199], v[86:89], v[106:109], v[196:199]
	ds_read_b128 v[106:109], v112 offset:12544
	v_fmac_f32_e32 v201, v225, v129
	v_max_i32_e32 v224, 0, v6
	v_fmac_f32_e32 v201, v224, v130
	v_mfma_f32_16x16x32_bf16 v[184:187], v[74:77], v[102:105], v[184:187]
	v_max_i32_e32 v225, 0, v7
	v_fmac_f32_e32 v201, v225, v131
	v_max_i32_e32 v224, 0, v12
	v_mfma_f32_16x16x32_bf16 v[192:195], v[94:97], v[102:105], v[192:195]
	ds_read_b128 v[102:105], v112 offset:14336
	v_fmac_f32_e32 v201, v224, v132
	v_max_i32_e32 v225, 0, v13
	v_fmac_f32_e32 v201, v225, v133
	v_mfma_f32_16x16x32_bf16 v[188:191], v[74:77], v[98:101], v[188:191]
	v_max_i32_e32 v224, 0, v14
	v_fmac_f32_e32 v201, v224, v134
	v_mfma_f32_16x16x32_bf16 v[196:199], v[94:97], v[98:101], v[196:199]
	ds_read_b128 v[98:101], v112 offset:14592
	v_max_i32_e32 v225, 0, v15
	v_fmac_f32_e32 v201, v225, v135
	s_waitcnt lgkmcnt(7)
	v_mfma_f32_16x16x32_bf16 v[0:3], v[58:61], v[160:163], 0
	v_mfma_f32_16x16x32_bf16 v[8:11], v[28:31], v[160:163], 0
	s_waitcnt lgkmcnt(6)
	v_mfma_f32_16x16x32_bf16 v[4:7], v[58:61], v[164:167], 0
	v_mfma_f32_16x16x32_bf16 v[12:15], v[28:31], v[164:167], 0
	v_max_i32_e32 v226, 0, v184
	v_fma_f32 v202, v226, v136, 0
	s_waitcnt lgkmcnt(5)
	v_mfma_f32_16x16x32_bf16 v[0:3], v[16:19], v[168:171], v[0:3]
	v_max_i32_e32 v227, 0, v185
	v_fmac_f32_e32 v202, v227, v137
	v_mfma_f32_16x16x32_bf16 v[8:11], v[50:53], v[168:171], v[8:11]
	v_max_i32_e32 v226, 0, v186
	v_fmac_f32_e32 v202, v226, v138
	s_waitcnt lgkmcnt(4)
	v_mfma_f32_16x16x32_bf16 v[4:7], v[16:19], v[172:175], v[4:7]
	v_max_i32_e32 v227, 0, v187
	v_fmac_f32_e32 v202, v227, v139
	v_mfma_f32_16x16x32_bf16 v[12:15], v[50:53], v[172:175], v[12:15]
	v_max_i32_e32 v226, 0, v192
	v_fmac_f32_e32 v202, v226, v140
	s_waitcnt lgkmcnt(3)
	v_mfma_f32_16x16x32_bf16 v[0:3], v[20:23], v[176:179], v[0:3]
	v_max_i32_e32 v227, 0, v193
	v_fmac_f32_e32 v202, v227, v141
	v_mfma_f32_16x16x32_bf16 v[8:11], v[54:57], v[176:179], v[8:11]
	v_max_i32_e32 v226, 0, v194
	v_fmac_f32_e32 v202, v226, v142
	v_max_i32_e32 v227, 0, v195
	s_waitcnt lgkmcnt(2)
	v_mfma_f32_16x16x32_bf16 v[4:7], v[20:23], v[106:109], v[4:7]
	v_fmac_f32_e32 v202, v227, v143
	v_max_i32_e32 v226, 0, v188
	v_fma_f32 v203, v226, v136, 0
	v_mfma_f32_16x16x32_bf16 v[12:15], v[54:57], v[106:109], v[12:15]
	v_max_i32_e32 v227, 0, v189
	v_fmac_f32_e32 v203, v227, v137
	v_max_i32_e32 v226, 0, v190
	s_waitcnt lgkmcnt(1)
	v_mfma_f32_16x16x32_bf16 v[0:3], v[24:27], v[102:105], v[0:3]
	v_fmac_f32_e32 v203, v226, v138
	v_max_i32_e32 v227, 0, v191
	v_fmac_f32_e32 v203, v227, v139
	v_mfma_f32_16x16x32_bf16 v[8:11], v[62:65], v[102:105], v[8:11]
	v_max_i32_e32 v226, 0, v196
	v_fmac_f32_e32 v203, v226, v140
	v_max_i32_e32 v227, 0, v197
	s_waitcnt lgkmcnt(0)
	v_mfma_f32_16x16x32_bf16 v[4:7], v[24:27], v[98:101], v[4:7]
	v_fmac_f32_e32 v203, v227, v141
	v_max_i32_e32 v226, 0, v198
	v_fmac_f32_e32 v203, v226, v142
	v_mfma_f32_16x16x32_bf16 v[12:15], v[62:65], v[98:101], v[12:15]
	v_max_i32_e32 v227, 0, v199
	v_fmac_f32_e32 v203, v227, v143
	v_mfma_f32_16x16x32_bf16 v[184:187], v[90:93], v[160:163], 0
	v_mfma_f32_16x16x32_bf16 v[192:195], v[78:81], v[160:163], 0
	ds_read_b128 v[160:163], v112 offset:16384
	v_mfma_f32_16x16x32_bf16 v[188:191], v[90:93], v[164:167], 0
	v_mfma_f32_16x16x32_bf16 v[196:199], v[78:81], v[164:167], 0
	ds_read_b128 v[164:167], v112 offset:16640
	v_mfma_f32_16x16x32_bf16 v[184:187], v[66:69], v[168:171], v[184:187]
	v_max_i32_e32 v224, 0, v0
	v_fma_f32 v218, v224, v128, 0
	v_mfma_f32_16x16x32_bf16 v[192:195], v[82:85], v[168:171], v[192:195]
	ds_read_b128 v[168:171], v112 offset:18432
	v_max_i32_e32 v225, 0, v1
	v_fmac_f32_e32 v218, v225, v129
	v_mfma_f32_16x16x32_bf16 v[188:191], v[66:69], v[172:175], v[188:191]
	v_max_i32_e32 v224, 0, v2
	v_fmac_f32_e32 v218, v224, v130
	v_max_i32_e32 v225, 0, v3
	v_mfma_f32_16x16x32_bf16 v[196:199], v[82:85], v[172:175], v[196:199]
	ds_read_b128 v[172:175], v112 offset:18688
	v_fmac_f32_e32 v218, v225, v131
	v_max_i32_e32 v224, 0, v8
	v_fmac_f32_e32 v218, v224, v132
	v_mfma_f32_16x16x32_bf16 v[184:187], v[70:73], v[176:179], v[184:187]
	v_max_i32_e32 v225, 0, v9
	v_fmac_f32_e32 v218, v225, v133
	v_max_i32_e32 v224, 0, v10
	v_mfma_f32_16x16x32_bf16 v[192:195], v[86:89], v[176:179], v[192:195]
	ds_read_b128 v[176:179], v112 offset:20480
	v_fmac_f32_e32 v218, v224, v134
	v_max_i32_e32 v225, 0, v11
	v_fmac_f32_e32 v218, v225, v135
	v_mfma_f32_16x16x32_bf16 v[188:191], v[70:73], v[106:109], v[188:191]
	v_max_i32_e32 v224, 0, v4
	v_fma_f32 v219, v224, v128, 0
	v_max_i32_e32 v225, 0, v5
	v_mfma_f32_16x16x32_bf16 v[196:199], v[86:89], v[106:109], v[196:199]
	ds_read_b128 v[106:109], v112 offset:20736
	v_fmac_f32_e32 v219, v225, v129
	v_max_i32_e32 v224, 0, v6
	v_fmac_f32_e32 v219, v224, v130
	v_mfma_f32_16x16x32_bf16 v[184:187], v[74:77], v[102:105], v[184:187]
	v_max_i32_e32 v225, 0, v7
	v_fmac_f32_e32 v219, v225, v131
	v_max_i32_e32 v224, 0, v12
	v_mfma_f32_16x16x32_bf16 v[192:195], v[94:97], v[102:105], v[192:195]
	ds_read_b128 v[102:105], v112 offset:22528
	v_fmac_f32_e32 v219, v224, v132
	v_max_i32_e32 v225, 0, v13
	v_fmac_f32_e32 v219, v225, v133
	v_mfma_f32_16x16x32_bf16 v[188:191], v[74:77], v[98:101], v[188:191]
	v_max_i32_e32 v224, 0, v14
	v_fmac_f32_e32 v219, v224, v134
	v_mfma_f32_16x16x32_bf16 v[196:199], v[94:97], v[98:101], v[196:199]
	ds_read_b128 v[98:101], v112 offset:22784
	v_max_i32_e32 v225, 0, v15
	v_fmac_f32_e32 v219, v225, v135
	s_waitcnt lgkmcnt(7)
; __device__ __forceinline__ void ph_indexer(const Params& p, char* shm) {
;     ...
;           IDX_TILE(ktp * 2, pr0);
;           __builtin_amdgcn_sched_barrier(0);
;           IDX_TILE(ktp * 2 + 1, pr1);
;           __builtin_amdgcn_sched_barrier(0);
;     ...
; #pragma unroll
;           for (int q = 0; q < 2; ++q) {
;             const float mine = half ? pr1[q] : pr0[q];
;             const float send = half ? pr0[q] : pr1[q];
;             const float recv = __shfl_xor(send, 32);
;             p.SC[(rowb + wid * 2 + q) * L + st * 128 + ktp * 64 + lane] = mine + recv;
;           }
	v_mfma_f32_16x16x32_bf16 v[0:3], v[58:61], v[160:163], 0
	v_mfma_f32_16x16x32_bf16 v[8:11], v[28:31], v[160:163], 0
	s_waitcnt lgkmcnt(6)
	v_mfma_f32_16x16x32_bf16 v[4:7], v[58:61], v[164:167], 0
	v_mfma_f32_16x16x32_bf16 v[12:15], v[28:31], v[164:167], 0
	v_max_i32_e32 v226, 0, v184
	v_fma_f32 v220, v226, v136, 0
	s_waitcnt lgkmcnt(5)
	v_mfma_f32_16x16x32_bf16 v[0:3], v[16:19], v[168:171], v[0:3]
	v_max_i32_e32 v227, 0, v185
	v_fmac_f32_e32 v220, v227, v137
	v_mfma_f32_16x16x32_bf16 v[8:11], v[50:53], v[168:171], v[8:11]
	v_max_i32_e32 v226, 0, v186
	v_fmac_f32_e32 v220, v226, v138
	s_waitcnt lgkmcnt(4)
	v_mfma_f32_16x16x32_bf16 v[4:7], v[16:19], v[172:175], v[4:7]
	v_max_i32_e32 v227, 0, v187
	v_fmac_f32_e32 v220, v227, v139
	v_mfma_f32_16x16x32_bf16 v[12:15], v[50:53], v[172:175], v[12:15]
	v_max_i32_e32 v226, 0, v192
	v_fmac_f32_e32 v220, v226, v140
	s_waitcnt lgkmcnt(3)
	v_mfma_f32_16x16x32_bf16 v[0:3], v[20:23], v[176:179], v[0:3]
	v_max_i32_e32 v227, 0, v193
	v_fmac_f32_e32 v220, v227, v141
	v_mfma_f32_16x16x32_bf16 v[8:11], v[54:57], v[176:179], v[8:11]
	v_max_i32_e32 v226, 0, v194
	v_fmac_f32_e32 v220, v226, v142
	v_max_i32_e32 v227, 0, v195
	s_waitcnt lgkmcnt(2)
	v_mfma_f32_16x16x32_bf16 v[4:7], v[20:23], v[106:109], v[4:7]
	v_fmac_f32_e32 v220, v227, v143
	v_max_i32_e32 v226, 0, v188
	v_fma_f32 v221, v226, v136, 0
	v_mfma_f32_16x16x32_bf16 v[12:15], v[54:57], v[106:109], v[12:15]
	v_max_i32_e32 v227, 0, v189
	v_fmac_f32_e32 v221, v227, v137
	v_max_i32_e32 v226, 0, v190
	s_waitcnt lgkmcnt(1)
	v_mfma_f32_16x16x32_bf16 v[0:3], v[24:27], v[102:105], v[0:3]
	v_fmac_f32_e32 v221, v226, v138
	v_max_i32_e32 v227, 0, v191
	v_fmac_f32_e32 v221, v227, v139
	v_mfma_f32_16x16x32_bf16 v[8:11], v[62:65], v[102:105], v[8:11]
	v_max_i32_e32 v226, 0, v196
	v_fmac_f32_e32 v221, v226, v140
	v_max_i32_e32 v227, 0, v197
	s_waitcnt lgkmcnt(0)
	v_mfma_f32_16x16x32_bf16 v[4:7], v[24:27], v[98:101], v[4:7]
	v_fmac_f32_e32 v221, v227, v141
	v_max_i32_e32 v226, 0, v198
	v_fmac_f32_e32 v221, v226, v142
	v_mfma_f32_16x16x32_bf16 v[12:15], v[62:65], v[98:101], v[12:15]
	v_max_i32_e32 v227, 0, v199
	v_fmac_f32_e32 v221, v227, v143
	v_mfma_f32_16x16x32_bf16 v[184:187], v[90:93], v[160:163], 0
	s_nop 1
	v_permlane16_swap_b32_e32 v200, v201
	v_permlane16_swap_b32_e32 v218, v219
	v_permlane16_swap_b32_e32 v202, v203
	v_mfma_f32_16x16x32_bf16 v[192:195], v[78:81], v[160:163], 0
	ds_read_b128 v[160:163], v112 offset:24576
	v_permlane16_swap_b32_e32 v220, v221
	v_add_f32_e32 v200, v200, v201
	v_add_f32_e32 v218, v218, v219
	v_add_f32_e32 v202, v202, v203
	v_mfma_f32_16x16x32_bf16 v[188:191], v[90:93], v[164:167], 0
	v_add_f32_e32 v220, v220, v221
	s_nop 1
	v_permlane32_swap_b32_e32 v200, v218
	v_permlane32_swap_b32_e32 v202, v220
	v_mfma_f32_16x16x32_bf16 v[196:199], v[78:81], v[164:167], 0
	ds_read_b128 v[164:167], v112 offset:24832
	v_add_f32_e32 v200, v200, v218
	v_add_f32_e32 v202, v202, v220
	global_store_dword v[228:229], v200, off nt
	global_store_dword v[230:231], v202, off nt
	v_mfma_f32_16x16x32_bf16 v[184:187], v[66:69], v[168:171], v[184:187]
	v_max_i32_e32 v224, 0, v0
	v_fma_f32 v222, v224, v128, 0
	v_mfma_f32_16x16x32_bf16 v[192:195], v[82:85], v[168:171], v[192:195]
	ds_read_b128 v[168:171], v112 offset:26624
	v_max_i32_e32 v225, 0, v1
	v_fmac_f32_e32 v222, v225, v129
	v_mfma_f32_16x16x32_bf16 v[188:191], v[66:69], v[172:175], v[188:191]
	v_max_i32_e32 v224, 0, v2
	v_fmac_f32_e32 v222, v224, v130
	v_max_i32_e32 v225, 0, v3
	v_mfma_f32_16x16x32_bf16 v[196:199], v[82:85], v[172:175], v[196:199]
	ds_read_b128 v[172:175], v112 offset:26880
	v_fmac_f32_e32 v222, v225, v131
	v_max_i32_e32 v224, 0, v8
	v_fmac_f32_e32 v222, v224, v132
	v_mfma_f32_16x16x32_bf16 v[184:187], v[70:73], v[176:179], v[184:187]
	v_max_i32_e32 v225, 0, v9
	v_fmac_f32_e32 v222, v225, v133
	v_max_i32_e32 v224, 0, v10
	v_mfma_f32_16x16x32_bf16 v[192:195], v[86:89], v[176:179], v[192:195]
	ds_read_b128 v[176:179], v112 offset:28672
	v_fmac_f32_e32 v222, v224, v134
	v_max_i32_e32 v225, 0, v11
	v_fmac_f32_e32 v222, v225, v135
	v_mfma_f32_16x16x32_bf16 v[188:191], v[70:73], v[106:109], v[188:191]
	v_max_i32_e32 v224, 0, v4
	v_fma_f32 v223, v224, v128, 0
	v_max_i32_e32 v225, 0, v5
	v_mfma_f32_16x16x32_bf16 v[196:199], v[86:89], v[106:109], v[196:199]
	ds_read_b128 v[106:109], v112 offset:28928
	v_fmac_f32_e32 v223, v225, v129
	v_max_i32_e32 v224, 0, v6
	v_fmac_f32_e32 v223, v224, v130
	v_mfma_f32_16x16x32_bf16 v[184:187], v[74:77], v[102:105], v[184:187]
	v_max_i32_e32 v225, 0, v7
	v_fmac_f32_e32 v223, v225, v131
	v_max_i32_e32 v224, 0, v12
	v_mfma_f32_16x16x32_bf16 v[192:195], v[94:97], v[102:105], v[192:195]
	ds_read_b128 v[102:105], v112 offset:30720
	v_fmac_f32_e32 v223, v224, v132
	v_max_i32_e32 v225, 0, v13
	v_fmac_f32_e32 v223, v225, v133
	v_mfma_f32_16x16x32_bf16 v[188:191], v[74:77], v[98:101], v[188:191]
	v_max_i32_e32 v224, 0, v14
	v_fmac_f32_e32 v223, v224, v134
	v_mfma_f32_16x16x32_bf16 v[196:199], v[94:97], v[98:101], v[196:199]
	ds_read_b128 v[98:101], v112 offset:30976
	v_max_i32_e32 v225, 0, v15
	v_fmac_f32_e32 v223, v225, v135
	s_waitcnt lgkmcnt(7)
; #define WAIT_V0() asm volatile("s_waitcnt vmcnt(0)" ::: "memory")
; #define WAIT_L0() asm volatile("s_waitcnt lgkmcnt(0)" ::: "memory")
; __device__ __forceinline__ void ph_indexer(const Params& p, char* shm) {
;     ...
;       for (int st = 0; st < nst; ++st) {
;         if (st == 0) WAIT_V0(); else asm volatile("s_waitcnt vmcnt(4)" ::: "memory");
;         WAIT_L0();
;         __builtin_amdgcn_s_barrier();
;         if (st + 1 < nst) IDX_STAGE((st + 1) & 1, st + 1);
	v_mfma_f32_16x16x32_bf16 v[0:3], v[58:61], v[160:163], 0
	v_mfma_f32_16x16x32_bf16 v[8:11], v[28:31], v[160:163], 0
	s_waitcnt lgkmcnt(6)
	v_mfma_f32_16x16x32_bf16 v[4:7], v[58:61], v[164:167], 0
	v_mfma_f32_16x16x32_bf16 v[12:15], v[28:31], v[164:167], 0
	v_max_i32_e32 v226, 0, v184
	v_fma_f32 v202, v226, v136, 0
	s_waitcnt lgkmcnt(5)
	v_mfma_f32_16x16x32_bf16 v[0:3], v[16:19], v[168:171], v[0:3]
	v_max_i32_e32 v227, 0, v185
	v_fmac_f32_e32 v202, v227, v137
	v_mfma_f32_16x16x32_bf16 v[8:11], v[50:53], v[168:171], v[8:11]
	v_max_i32_e32 v226, 0, v186
	v_fmac_f32_e32 v202, v226, v138
	s_waitcnt lgkmcnt(4)
	v_mfma_f32_16x16x32_bf16 v[4:7], v[16:19], v[172:175], v[4:7]
	v_max_i32_e32 v227, 0, v187
	v_fmac_f32_e32 v202, v227, v139
	v_mfma_f32_16x16x32_bf16 v[12:15], v[50:53], v[172:175], v[12:15]
	v_max_i32_e32 v226, 0, v192
	v_fmac_f32_e32 v202, v226, v140
	s_waitcnt lgkmcnt(3)
	v_mfma_f32_16x16x32_bf16 v[0:3], v[20:23], v[176:179], v[0:3]
	v_max_i32_e32 v227, 0, v193
	v_fmac_f32_e32 v202, v227, v141
	v_mfma_f32_16x16x32_bf16 v[8:11], v[54:57], v[176:179], v[8:11]
	v_max_i32_e32 v226, 0, v194
	v_fmac_f32_e32 v202, v226, v142
	v_max_i32_e32 v227, 0, v195
	s_waitcnt lgkmcnt(2)
	v_mfma_f32_16x16x32_bf16 v[4:7], v[20:23], v[106:109], v[4:7]
	v_fmac_f32_e32 v202, v227, v143
	v_max_i32_e32 v226, 0, v188
	v_fma_f32 v203, v226, v136, 0
	v_mfma_f32_16x16x32_bf16 v[12:15], v[54:57], v[106:109], v[12:15]
	v_max_i32_e32 v227, 0, v189
	v_fmac_f32_e32 v203, v227, v137
	v_max_i32_e32 v226, 0, v190
	s_waitcnt lgkmcnt(1)
	v_mfma_f32_16x16x32_bf16 v[0:3], v[24:27], v[102:105], v[0:3]
	v_fmac_f32_e32 v203, v226, v138
	v_max_i32_e32 v227, 0, v191
	v_fmac_f32_e32 v203, v227, v139
	v_mfma_f32_16x16x32_bf16 v[8:11], v[62:65], v[102:105], v[8:11]
	v_max_i32_e32 v226, 0, v196
	v_fmac_f32_e32 v203, v226, v140
	v_max_i32_e32 v227, 0, v197
	s_waitcnt lgkmcnt(0)
	v_mfma_f32_16x16x32_bf16 v[4:7], v[24:27], v[98:101], v[4:7]
	v_fmac_f32_e32 v203, v227, v141
	v_max_i32_e32 v226, 0, v198
	v_fmac_f32_e32 v203, v226, v142
	v_mfma_f32_16x16x32_bf16 v[12:15], v[62:65], v[98:101], v[12:15]
	v_max_i32_e32 v227, 0, v199
	v_fmac_f32_e32 v203, v227, v143
	v_mfma_f32_16x16x32_bf16 v[184:187], v[90:93], v[160:163], 0
	v_mfma_f32_16x16x32_bf16 v[192:195], v[78:81], v[160:163], 0
	v_mfma_f32_16x16x32_bf16 v[188:191], v[90:93], v[164:167], 0
	v_mfma_f32_16x16x32_bf16 v[196:199], v[78:81], v[164:167], 0
	v_mfma_f32_16x16x32_bf16 v[184:187], v[66:69], v[168:171], v[184:187]
	v_max_i32_e32 v224, 0, v0
	v_fma_f32 v218, v224, v128, 0
	v_mfma_f32_16x16x32_bf16 v[192:195], v[82:85], v[168:171], v[192:195]
	v_max_i32_e32 v225, 0, v1
	v_fmac_f32_e32 v218, v225, v129
	v_mfma_f32_16x16x32_bf16 v[188:191], v[66:69], v[172:175], v[188:191]
	v_max_i32_e32 v224, 0, v2
	v_fmac_f32_e32 v218, v224, v130
	v_max_i32_e32 v225, 0, v3
	v_mfma_f32_16x16x32_bf16 v[196:199], v[82:85], v[172:175], v[196:199]
	v_fmac_f32_e32 v218, v225, v131
	v_max_i32_e32 v224, 0, v8
	v_fmac_f32_e32 v218, v224, v132
	v_mfma_f32_16x16x32_bf16 v[184:187], v[70:73], v[176:179], v[184:187]
	v_max_i32_e32 v225, 0, v9
	v_fmac_f32_e32 v218, v225, v133
	v_max_i32_e32 v224, 0, v10
	v_mfma_f32_16x16x32_bf16 v[192:195], v[86:89], v[176:179], v[192:195]
	v_fmac_f32_e32 v218, v224, v134
	v_max_i32_e32 v225, 0, v11
	v_fmac_f32_e32 v218, v225, v135
	v_mfma_f32_16x16x32_bf16 v[188:191], v[70:73], v[106:109], v[188:191]
	v_max_i32_e32 v224, 0, v4
	v_fma_f32 v219, v224, v128, 0
	v_max_i32_e32 v225, 0, v5
	v_mfma_f32_16x16x32_bf16 v[196:199], v[86:89], v[106:109], v[196:199]
	v_fmac_f32_e32 v219, v225, v129
	v_max_i32_e32 v224, 0, v6
	v_fmac_f32_e32 v219, v224, v130
	v_mfma_f32_16x16x32_bf16 v[184:187], v[74:77], v[102:105], v[184:187]
	v_max_i32_e32 v225, 0, v7
	v_fmac_f32_e32 v219, v225, v131
	v_max_i32_e32 v224, 0, v12
	v_mfma_f32_16x16x32_bf16 v[192:195], v[94:97], v[102:105], v[192:195]
	v_fmac_f32_e32 v219, v224, v132
	v_max_i32_e32 v225, 0, v13
	v_fmac_f32_e32 v219, v225, v133
	v_mfma_f32_16x16x32_bf16 v[188:191], v[74:77], v[98:101], v[188:191]
	v_max_i32_e32 v224, 0, v14
	v_fmac_f32_e32 v219, v224, v134
	v_mfma_f32_16x16x32_bf16 v[196:199], v[94:97], v[98:101], v[196:199]
	v_max_i32_e32 v225, 0, v15
	v_fmac_f32_e32 v219, v225, v135
	s_cmp_lg_u32 s20, s22
	s_cbranch_scc0 .Lidx_flush_s1
	s_mov_b32 s4, s20
	s_waitcnt vmcnt(2)
	s_waitcnt lgkmcnt(0)
	s_add_i32 s20, s4, 1
	s_barrier
	s_branch .LBB0_943
